# P2 hg_state_item: next-item tile loads spread through the gate pass (saddr), state-row stores read LDS 3 rows ahead
# speedup vs baseline: 1.0069x; 1.0069x over previous
.LBB0_271:
	s_cmpk_gt_i32 s8, 0x7ff
	s_cbranch_scc1 .LBB0_290
	s_lshl_b32 s9, s8, 23
	s_and_b32 s9, s9, 0x1800000
	s_add_u32 s9, s86, s9
	s_addc_u32 s14, s87, 0
	s_add_u32 s10, s9, 0xa000000
	v_add_u32_e32 v64, 0x200, v62
	s_addc_u32 s11, s14, 0
	s_ashr_i32 s12, s8, 2
	v_ashrrev_i32_e32 v63, 31, v62
	v_ashrrev_i32_e32 v65, 31, v64
	s_ashr_i32 s13, s12, 31
	v_lshlrev_b64 v[58:59], 3, v[62:63]
	v_lshlrev_b64 v[60:61], 3, v[64:65]
	s_lshl_b64 s[12:13], s[12:13], 13
	s_waitcnt vmcnt(0)
	v_lshl_add_u64 v[2:3], s[12:13], 0, v[58:59]
	v_lshl_add_u64 v[4:5], s[12:13], 0, v[60:61]
	v_lshlrev_b64 v[18:19], 1, v[2:3]
	v_lshlrev_b64 v[20:21], 1, v[4:5]
	v_lshl_add_u64 v[2:3], s[10:11], 0, v[18:19]
	v_lshl_add_u64 v[6:7], s[10:11], 0, v[20:21]
	s_add_u32 s10, s9, 0xc000000
	s_addc_u32 s11, s14, 0
	v_lshl_add_u64 v[10:11], s[10:11], 0, v[18:19]
	v_lshl_add_u64 v[14:15], s[10:11], 0, v[20:21]
	s_add_u32 s10, s9, 0xe000000
	s_addc_u32 s11, s14, 0
	v_lshl_add_u64 v[18:19], s[10:11], 0, v[18:19]
	v_lshl_add_u64 v[22:23], s[10:11], 0, v[20:21]
	global_load_dwordx4 v[2:5], v[2:3], off
	s_nop 0
	global_load_dwordx4 v[6:9], v[6:7], off
	s_nop 0
	global_load_dwordx4 v[10:13], v[10:11], off
	s_nop 0
	global_load_dwordx4 v[14:17], v[14:15], off
	s_nop 0
	global_load_dwordx4 v[18:21], v[18:19], off
	s_nop 0
	global_load_dwordx4 v[22:25], v[22:23], off
	v_lshlrev_b32_e32 v63, 3, v62
	v_and_b32_e32 v0, 0x78, v63
	v_ashrrev_i32_e32 v26, 4, v62
	s_movk_i32 s9, 0x88
	v_mad_u64_u32 v[28:29], s[10:11], v26, s9, v[0:1]
	v_lshl_add_u32 v90, v28, 1, 0
	v_ashrrev_i32_e32 v28, 4, v64
	v_mad_u64_u32 v[30:31], s[10:11], v28, s9, v[0:1]
	s_add_i32 s9, 0, 0x4400
	s_movk_i32 s10, 0x100
	v_and_b32_e32 v27, 63, v62
	v_mov_b32_e32 v29, s9
	v_cmp_gt_u32_e32 vcc, s10, v62
	v_lshlrev_b32_e32 v32, 2, v27
	v_lshl_add_u32 v92, v30, 1, 0
	v_cndmask_b32_e64 v29, v29, 0, vcc
	v_add_u32_e32 v93, v29, v32
	v_ashrrev_i32_e32 v29, 6, v62
	v_and_b32_e32 v108, -4, v29
	v_lshl_or_b32 v34, v29, 9, v180
	v_ashrrev_i32_e32 v30, 7, v62
	v_lshlrev_b32_e32 v29, 2, v62
	v_lshl_add_u32 v109, v27, 3, 0
	v_lshlrev_b32_e32 v27, 11, v30
	v_and_b32_e32 v35, 0x1fc, v29
	v_add3_u32 v110, 0, v27, v35
	s_ashr_i32 s24, s3, 8
	s_bfe_u32 s3, s3, 0x20006
	v_bfe_u32 v27, v62, 4, 2
	s_cmp_lt_u32 s17, 4
	v_bfe_u32 v29, v62, 2, 2
	v_lshlrev_b32_e32 v91, 2, v27
	v_cmp_gt_i32_e64 s[40:41], s10, v62
	s_cselect_b32 s9, 0, s9
	v_lshl_or_b32 v88, v27, 3, v29
	s_lshl_b32 s10, s3, 6
	v_lshl_or_b32 v27, s3, 5, v91
	s_lshl_b32 s3, s24, 11
	s_add_i32 s3, s3, 0
	v_lshlrev_b32_e32 v0, 1, v0
	v_and_b32_e32 v65, 15, v62
	v_and_b32_e32 v29, 12, v32
	v_lshl_add_u32 v111, v27, 2, s3
	v_lshl_add_u32 v112, v27, 1, 0
	v_add_u32_e32 v44, 0, v0
	v_lshl_add_u64 v[66:67], s[46:47], 0, v[0:1]
	v_ashrrev_i32_e32 v27, 31, v26
	v_add_u32_e32 v0, 0x400, v62
	v_lshlrev_b32_e32 v89, 1, v29
	v_lshl_or_b32 v29, s24, 7, v65
	v_mul_lo_u32 v45, v26, s18
	v_lshlrev_b64 v[68:69], 8, v[26:27]
	v_ashrrev_i32_e32 v26, 4, v0
	v_mul_lo_u32 v113, v29, s18
	v_ashrrev_i32_e32 v29, 31, v28
	v_ashrrev_i32_e32 v27, 31, v26
	v_add_u32_e32 v0, 0x600, v62
	v_mul_lo_u32 v46, v28, s18
	v_lshlrev_b64 v[70:71], 8, v[28:29]
	v_mul_lo_u32 v28, v26, s18
	v_lshlrev_b64 v[72:73], 8, v[26:27]
	v_ashrrev_i32_e32 v26, 4, v0
	v_ashrrev_i32_e32 v27, 31, v26
	v_add_u32_e32 v0, 0x800, v62
	v_mul_lo_u32 v29, v26, s18
	v_lshlrev_b64 v[74:75], 8, v[26:27]
	v_ashrrev_i32_e32 v26, 4, v0
	v_ashrrev_i32_e32 v27, 31, v26
	v_add_u32_e32 v0, 0xa00, v62
	v_mul_lo_u32 v47, v26, s18
	v_lshlrev_b64 v[76:77], 8, v[26:27]
	v_ashrrev_i32_e32 v26, 4, v0
	v_ashrrev_i32_e32 v27, 31, v26
	v_add_u32_e32 v0, 0xc00, v62
	v_mul_lo_u32 v48, v26, s18
	v_lshlrev_b64 v[78:79], 8, v[26:27]
	v_ashrrev_i32_e32 v26, 4, v0
	s_add_i32 s9, s9, s10
	v_ashrrev_i32_e32 v27, 31, v26
	v_add_u32_e32 v0, 0xe00, v62
	v_ashrrev_i32_e32 v31, 31, v30
	v_add_u32_e32 v32, s9, v89
	v_mul_lo_u32 v49, v26, s18
	v_lshlrev_b64 v[80:81], 8, v[26:27]
	v_ashrrev_i32_e32 v26, 4, v0
	s_ashr_i32 s9, s8, 31
	v_lshlrev_b64 v[30:31], 9, v[30:31]
	v_ashrrev_i32_e32 v27, 31, v26
	s_lshl_b64 s[10:11], s[8:9], 10
	v_mul_lo_u32 v50, v26, s18
	v_lshlrev_b64 v[82:83], 8, v[26:27]
	v_lshl_add_u64 v[26:27], s[10:11], 0, v[30:31]
	v_lshlrev_b32_e32 v33, 9, v108
	v_add_u32_e32 v36, 0, v89
	v_mul_u32_u24_e32 v37, 0x110, v88
	v_add_u32_e32 v38, 0x2200, v113
	v_add_u32_e32 v39, 0x3300, v113
	v_add_u32_e32 v40, 0x4400, v113
	v_add_u32_e32 v41, 0x5500, v113
	v_add_u32_e32 v42, 0x6600, v113
	v_add_u32_e32 v43, 0x7700, v113
	s_ashr_i32 s3, s2, 31
	v_or_b32_e32 v26, v26, v35
	v_cndmask_b32_e64 v94, 14, 1, vcc
	v_cndmask_b32_e64 v95, 13, 2, vcc
	v_cndmask_b32_e64 v96, 12, 3, vcc
	v_cndmask_b32_e64 v97, 11, 4, vcc
	v_cndmask_b32_e64 v98, 10, 5, vcc
	v_cndmask_b32_e64 v99, 9, 6, vcc
	v_cndmask_b32_e64 v100, 8, 7, vcc
	v_cndmask_b32_e64 v101, 7, 8, vcc
	v_cndmask_b32_e64 v102, 6, 9, vcc
	v_cndmask_b32_e64 v103, 5, 10, vcc
	v_cndmask_b32_e64 v104, 4, 11, vcc
	v_cndmask_b32_e64 v105, 3, 12, vcc
	v_cndmask_b32_e64 v106, 2, 13, vcc
	v_cndmask_b32_e64 v107, 1, 14, vcc
	v_lshl_add_u64 v[84:85], s[94:95], 0, v[26:27]
	s_lshl_b64 s[10:11], s[2:3], 10
	v_add_u32_e32 v0, v109, v34
	v_add_u32_e32 v114, v32, v37
	v_add_u32_e32 v115, v36, v37
	v_add_u32_e32 v116, v112, v38
	v_add_u32_e32 v117, v112, v39
	v_add_u32_e32 v118, v112, v40
	v_add_u32_e32 v119, v112, v41
	v_add_u32_e32 v120, v112, v42
	v_add_u32_e32 v121, v112, v43
	v_add_u32_e32 v122, v44, v45
	v_add_u32_e32 v123, v44, v46
	v_add_u32_e32 v124, v44, v28
	v_add_u32_e32 v125, v44, v29
	v_add_u32_e32 v126, v44, v47
	v_add_u32_e32 v127, v44, v48
	v_add_u32_e32 v128, v44, v49
	v_add_u32_e32 v129, v44, v50
	v_add_u32_e32 v130, v109, v33
	s_mov_b64 s[12:13], s[8:9]
	s_waitcnt vmcnt(0)
	v_lshlrev_b32_e32 v236, 4, v214
	v_add_u32_e32 v237, 0x2000000, v236
	v_add_u32_e32 v238, 0x4000000, v236
	v_add_u32_e32 v239, 0x2000, v236
	v_add_u32_e32 v240, 0x2002000, v236
	v_add_u32_e32 v241, 0x4002000, v236
	s_branch .LBB0_274
.LBB0_273:
	s_or_b64 exec, exec, s[42:43]
	ds_read_b64_tr_b16 v[28:29], v114 offset:1088
	ds_read_b64_tr_b16 v[26:27], v114
	ds_read_b64_tr_b16 v[30:31], v114 offset:32
	ds_read_b64_tr_b16 v[32:33], v114 offset:1120
	ds_read_b64_tr_b16 v[36:37], v115 offset:35904
	ds_read_b64_tr_b16 v[34:35], v115 offset:34816
	ds_read_b64_tr_b16 v[38:39], v115 offset:34848
	ds_read_b64_tr_b16 v[40:41], v115 offset:35936
	ds_read_b64_tr_b16 v[50:51], v115 offset:34880
	ds_read_b64_tr_b16 v[52:53], v115 offset:35968
	ds_read_b64_tr_b16 v[132:133], v115 offset:34912
	ds_read_b64_tr_b16 v[134:135], v115 offset:36000
	ds_read_b64_tr_b16 v[140:141], v115 offset:34944
	ds_read_b64_tr_b16 v[142:143], v115 offset:36032
	ds_read_b64_tr_b16 v[156:157], v115 offset:34976
	ds_read_b64_tr_b16 v[158:159], v115 offset:36064
	ds_read_b64_tr_b16 v[166:167], v115 offset:35008
	ds_read_b64_tr_b16 v[168:169], v115 offset:36096
	ds_read_b64_tr_b16 v[174:175], v115 offset:35040
	ds_read_b64_tr_b16 v[176:177], v115 offset:36128
	s_waitcnt lgkmcnt(14)
	v_mfma_f32_16x16x32_bf16 v[42:45], v[26:29], v[34:37], 0
	v_add_u32_e32 v131, v112, v113
	s_add_u32 s12, s12, s2
	s_addc_u32 s13, s13, s3
	s_waitcnt lgkmcnt(12)
	v_mfma_f32_16x16x32_bf16 v[46:49], v[26:29], v[38:41], 0
	v_lshl_add_u64 v[84:85], v[84:85], 0, s[10:11]
	s_cmpk_gt_i32 s12, 0x7ff
	s_waitcnt lgkmcnt(10)
	v_mfma_f32_16x16x32_bf16 v[54:57], v[26:29], v[50:53], 0
	s_waitcnt lgkmcnt(8)
	v_mfma_f32_16x16x32_bf16 v[136:139], v[26:29], v[132:135], 0
	s_waitcnt lgkmcnt(6)
	v_mfma_f32_16x16x32_bf16 v[152:155], v[26:29], v[140:143], 0
	s_waitcnt lgkmcnt(4)
	v_mfma_f32_16x16x32_bf16 v[162:165], v[26:29], v[156:159], 0
	s_waitcnt lgkmcnt(2)
	v_mfma_f32_16x16x32_bf16 v[170:173], v[26:29], v[166:169], 0
	s_waitcnt lgkmcnt(0)
	v_mfma_f32_16x16x32_bf16 v[198:201], v[26:29], v[174:177], 0
	ds_read_b64_tr_b16 v[202:203], v114 offset:8704
	ds_read_b64_tr_b16 v[204:205], v114 offset:9792
	ds_read_b64_tr_b16 v[206:207], v114 offset:8736
	ds_read_b64_tr_b16 v[208:209], v114 offset:9824
	ds_read_b64_tr_b16 v[26:27], v115 offset:43520
	ds_read_b64_tr_b16 v[28:29], v115 offset:44608
	v_mfma_f32_16x16x32_bf16 v[34:37], v[30:33], v[34:37], 0
	v_mfma_f32_16x16x32_bf16 v[38:41], v[30:33], v[38:41], 0
	v_mfma_f32_16x16x32_bf16 v[50:53], v[30:33], v[50:53], 0
	v_mfma_f32_16x16x32_bf16 v[132:135], v[30:33], v[132:135], 0
	v_mfma_f32_16x16x32_bf16 v[140:143], v[30:33], v[140:143], 0
	v_mfma_f32_16x16x32_bf16 v[156:159], v[30:33], v[156:159], 0
	v_mfma_f32_16x16x32_bf16 v[166:169], v[30:33], v[166:169], 0
	v_mfma_f32_16x16x32_bf16 v[174:177], v[30:33], v[174:177], 0
	ds_read_b64_tr_b16 v[30:31], v115 offset:43552
	ds_read_b64_tr_b16 v[32:33], v115 offset:44640
	s_waitcnt lgkmcnt(2)
	v_mfma_f32_16x16x32_bf16 v[210:213], v[202:205], v[26:29], v[42:45]
	v_mfma_f32_16x16x32_bf16 v[26:29], v[206:209], v[26:29], v[34:37]
	s_nop 2
	ds_read_b64_tr_b16 v[34:35], v115 offset:43584
	ds_read_b64_tr_b16 v[36:37], v115 offset:44672
	s_waitcnt lgkmcnt(2)
	v_mfma_f32_16x16x32_bf16 v[216:219], v[202:205], v[30:33], v[46:49]
	v_mfma_f32_16x16x32_bf16 v[30:33], v[206:209], v[30:33], v[38:41]
	s_nop 2
	ds_read_b64_tr_b16 v[38:39], v115 offset:43616
	ds_read_b64_tr_b16 v[40:41], v115 offset:44704
	ds_read_b64_tr_b16 v[42:43], v115 offset:43648
	ds_read_b64_tr_b16 v[44:45], v115 offset:44736
	ds_read_b64_tr_b16 v[46:47], v115 offset:43680
	ds_read_b64_tr_b16 v[48:49], v115 offset:44768
	s_waitcnt lgkmcnt(6)
	v_mfma_f32_16x16x32_bf16 v[220:223], v[202:205], v[34:37], v[54:57]
	v_mfma_f32_16x16x32_bf16 v[34:37], v[206:209], v[34:37], v[50:53]
	s_nop 2
	ds_read_b64_tr_b16 v[50:51], v115 offset:43712
	ds_read_b64_tr_b16 v[52:53], v115 offset:44800
	ds_read_b64_tr_b16 v[54:55], v115 offset:43744
	ds_read_b64_tr_b16 v[56:57], v115 offset:44832
	s_waitcnt lgkmcnt(8)
	v_mfma_f32_16x16x32_bf16 v[136:139], v[202:205], v[38:41], v[136:139]
	v_mfma_f32_16x16x32_bf16 v[38:41], v[206:209], v[38:41], v[132:135]
	s_waitcnt lgkmcnt(6)
	v_mfma_f32_16x16x32_bf16 v[132:135], v[202:205], v[42:45], v[152:155]
	v_mfma_f32_16x16x32_bf16 v[42:45], v[206:209], v[42:45], v[140:143]
	s_waitcnt lgkmcnt(4)
	v_mfma_f32_16x16x32_bf16 v[140:143], v[202:205], v[46:49], v[162:165]
	v_mfma_f32_16x16x32_bf16 v[46:49], v[206:209], v[46:49], v[156:159]
	s_waitcnt lgkmcnt(2)
	v_mfma_f32_16x16x32_bf16 v[152:155], v[202:205], v[50:53], v[170:173]
	v_mfma_f32_16x16x32_bf16 v[50:53], v[206:209], v[50:53], v[166:169]
	s_waitcnt lgkmcnt(0)
	v_mfma_f32_16x16x32_bf16 v[156:159], v[202:205], v[54:57], v[198:201]
	v_mfma_f32_16x16x32_bf16 v[54:57], v[206:209], v[54:57], v[174:177]
	ds_read_b128 v[162:165], v111 offset:52224
	ds_read_b128 v[166:169], v111 offset:52736
	ds_read_b128 v[170:173], v111 offset:53248
	ds_read_b128 v[174:177], v111 offset:53760
	s_waitcnt lgkmcnt(2)
	v_pk_mul_f32 v[144:145], v[162:163], v[166:167]
	v_pk_mul_f32 v[162:163], v[164:165], v[168:169]
	s_waitcnt lgkmcnt(0)
	v_pk_mul_f32 v[164:165], v[170:171], v[174:175]
	v_pk_mul_f32 v[166:167], v[172:173], v[176:177]
	v_pk_mul_f32 v[144:145], v[144:145], v[164:165]
	v_pk_mul_f32 v[162:163], v[162:163], v[166:167]
	v_pk_mul_f32 v[132:133], v[132:133], v[144:145]
	v_pk_mul_f32 v[134:135], v[134:135], v[162:163]
	v_cvt_pk_bf16_f32 v132, v132, v133
	v_cvt_pk_bf16_f32 v133, v134, v135
	v_pk_mul_f32 v[164:165], v[212:213], v[162:163]
	v_pk_mul_f32 v[166:167], v[210:211], v[144:145]
	ds_write_b64 v118, v[132:133] offset:57344
	v_pk_mul_f32 v[132:133], v[142:143], v[162:163]
	v_pk_mul_f32 v[134:135], v[140:141], v[144:145]
	v_cvt_pk_bf16_f32 v166, v166, v167
	v_cvt_pk_bf16_f32 v167, v164, v165
	v_cvt_pk_bf16_f32 v134, v134, v135
	v_cvt_pk_bf16_f32 v135, v132, v133
	ds_write_b64 v131, v[166:167] offset:57344
	v_pk_mul_f32 v[164:165], v[218:219], v[162:163]
	v_pk_mul_f32 v[166:167], v[216:217], v[144:145]
	ds_write_b64 v119, v[134:135] offset:57344
	v_pk_mul_f32 v[132:133], v[154:155], v[162:163]
	v_pk_mul_f32 v[134:135], v[152:153], v[144:145]
	v_cvt_pk_bf16_f32 v166, v166, v167
	v_cvt_pk_bf16_f32 v167, v164, v165
	v_cvt_pk_bf16_f32 v134, v134, v135
	v_cvt_pk_bf16_f32 v135, v132, v133
	ds_write_b64 v131, v[166:167] offset:61696
	v_pk_mul_f32 v[164:165], v[222:223], v[162:163]
	v_pk_mul_f32 v[166:167], v[220:221], v[144:145]
	v_pk_mul_f32 v[138:139], v[138:139], v[162:163]
	v_pk_mul_f32 v[136:137], v[136:137], v[144:145]
	ds_write_b64 v120, v[134:135] offset:57344
	v_pk_mul_f32 v[132:133], v[158:159], v[162:163]
	v_pk_mul_f32 v[134:135], v[156:157], v[144:145]
	v_cvt_pk_bf16_f32 v166, v166, v167
	v_cvt_pk_bf16_f32 v167, v164, v165
	v_cvt_pk_bf16_f32 v136, v136, v137
	v_cvt_pk_bf16_f32 v137, v138, v139
	v_cvt_pk_bf16_f32 v134, v134, v135
	v_cvt_pk_bf16_f32 v135, v132, v133
	ds_write_b64 v116, v[166:167] offset:57344
	ds_write_b64 v117, v[136:137] offset:57344
	ds_write_b64 v121, v[134:135] offset:57344
	ds_read_b128 v[132:135], v111 offset:52288
	ds_read_b128 v[136:139], v111 offset:52800
	ds_read_b128 v[140:143], v111 offset:53312
	ds_read_b128 v[152:155], v111 offset:53824
	s_waitcnt lgkmcnt(2)
	v_pk_mul_f32 v[132:133], v[132:133], v[136:137]
	v_pk_mul_f32 v[134:135], v[134:135], v[138:139]
	s_waitcnt lgkmcnt(0)
	v_pk_mul_f32 v[136:137], v[140:141], v[152:153]
	v_pk_mul_f32 v[138:139], v[142:143], v[154:155]
	v_pk_mul_f32 v[132:133], v[132:133], v[136:137]
	v_pk_mul_f32 v[134:135], v[134:135], v[138:139]
	v_pk_mul_f32 v[26:27], v[26:27], v[132:133]
	v_pk_mul_f32 v[28:29], v[28:29], v[134:135]
	v_cvt_pk_bf16_f32 v26, v26, v27
	v_cvt_pk_bf16_f32 v27, v28, v29
	ds_write_b64 v131, v[26:27] offset:57376
	v_pk_mul_f32 v[26:27], v[32:33], v[134:135]
	v_pk_mul_f32 v[28:29], v[30:31], v[132:133]
	s_nop 0
	v_cvt_pk_bf16_f32 v28, v28, v29
	v_cvt_pk_bf16_f32 v29, v26, v27
	ds_write_b64 v131, v[28:29] offset:61728
	v_pk_mul_f32 v[26:27], v[36:37], v[134:135]
	v_pk_mul_f32 v[28:29], v[34:35], v[132:133]
	s_nop 0
	v_cvt_pk_bf16_f32 v28, v28, v29
	v_cvt_pk_bf16_f32 v29, v26, v27
	ds_write_b64 v116, v[28:29] offset:57376
	v_pk_mul_f32 v[26:27], v[40:41], v[134:135]
	v_pk_mul_f32 v[28:29], v[38:39], v[132:133]
	s_nop 0
	v_cvt_pk_bf16_f32 v28, v28, v29
	v_cvt_pk_bf16_f32 v29, v26, v27
	ds_write_b64 v117, v[28:29] offset:57376
	v_pk_mul_f32 v[26:27], v[44:45], v[134:135]
	v_pk_mul_f32 v[28:29], v[42:43], v[132:133]
	s_nop 0
	v_cvt_pk_bf16_f32 v28, v28, v29
	v_cvt_pk_bf16_f32 v29, v26, v27
	ds_write_b64 v118, v[28:29] offset:57376
	v_pk_mul_f32 v[26:27], v[48:49], v[134:135]
	v_pk_mul_f32 v[28:29], v[46:47], v[132:133]
	s_nop 0
	v_cvt_pk_bf16_f32 v28, v28, v29
	v_cvt_pk_bf16_f32 v29, v26, v27
	ds_write_b64 v119, v[28:29] offset:57376
	v_pk_mul_f32 v[26:27], v[52:53], v[134:135]
	v_pk_mul_f32 v[28:29], v[50:51], v[132:133]
	s_nop 0
	v_cvt_pk_bf16_f32 v28, v28, v29
	v_cvt_pk_bf16_f32 v29, v26, v27
	ds_write_b64 v120, v[28:29] offset:57376
	v_pk_mul_f32 v[26:27], v[56:57], v[134:135]
	v_pk_mul_f32 v[28:29], v[54:55], v[132:133]
	s_nop 0
	v_cvt_pk_bf16_f32 v28, v28, v29
	v_cvt_pk_bf16_f32 v29, v26, v27
	v_lshlrev_b64 v[26:27], 16, v[86:87]
	ds_write_b64 v121, v[28:29] offset:57376
	s_waitcnt lgkmcnt(0)
	s_barrier
	v_lshl_add_u64 v[30:31], v[66:67], 0, v[26:27]
	ds_read_b128 v[26:29], v122 offset:57344
	ds_read_b128 v[224:227], v123 offset:57344
	ds_read_b128 v[228:231], v124 offset:57344
	ds_read_b128 v[232:235], v125 offset:57344
	v_lshl_add_u64 v[32:33], v[30:31], 0, v[68:69]
	s_waitcnt lgkmcnt(3)
	global_store_dwordx4 v[32:33], v[26:29], off
	v_lshl_add_u64 v[252:253], v[30:31], 0, v[70:71]
	ds_read_b128 v[26:29], v126 offset:57344
	s_waitcnt lgkmcnt(3)
	global_store_dwordx4 v[252:253], v[224:227], off
	v_lshl_add_u64 v[32:33], v[30:31], 0, v[72:73]
	ds_read_b128 v[224:227], v127 offset:57344
	s_waitcnt lgkmcnt(3)
	global_store_dwordx4 v[32:33], v[228:231], off
	v_lshl_add_u64 v[252:253], v[30:31], 0, v[74:75]
	ds_read_b128 v[228:231], v128 offset:57344
	s_waitcnt lgkmcnt(3)
	global_store_dwordx4 v[252:253], v[232:235], off
	v_lshl_add_u64 v[32:33], v[30:31], 0, v[76:77]
	ds_read_b128 v[232:235], v129 offset:57344
	s_waitcnt lgkmcnt(3)
	global_store_dwordx4 v[32:33], v[26:29], off
	v_lshl_add_u64 v[252:253], v[30:31], 0, v[78:79]
	s_waitcnt lgkmcnt(2)
	global_store_dwordx4 v[252:253], v[224:227], off
	v_lshl_add_u64 v[32:33], v[30:31], 0, v[80:81]
	s_waitcnt lgkmcnt(1)
	global_store_dwordx4 v[32:33], v[228:231], off
	v_lshl_add_u64 v[30:31], v[30:31], 0, v[82:83]
	s_waitcnt lgkmcnt(0)
	global_store_dwordx4 v[30:31], v[232:235], off
	s_barrier
	s_cbranch_scc1 .LBB0_286
.LBB0_274:
	s_add_i32 s14, s2, s12
	s_cmpk_lt_i32 s14, 0x800
	s_cselect_b32 s14, s14, -1
	s_cmp_lt_i32 s14, 0
	s_waitcnt vmcnt(8)
	ds_write_b128 v90, v[2:5]
	ds_write_b128 v90, v[10:13] offset:17408
	ds_write_b128 v90, v[18:21] offset:34816
	ds_write_b128 v92, v[6:9]
	ds_write_b128 v92, v[14:17] offset:17408
	ds_write_b128 v92, v[22:25] offset:34816
	s_waitcnt lgkmcnt(0)
	s_barrier
	s_cmp_lt_i32 s14, 0
	s_cselect_b32 s14, s12, s14
	s_lshr_b32 s15, s14, 2
	s_lshl_b32 s15, s15, 14
	s_and_b32 s14, s14, 3
	s_lshl_b32 s14, s14, 23
	s_add_u32 s14, s14, s15
	s_add_u32 s14, s14, 0xa000000
	s_add_u32 s100, s86, s14
	s_addc_u32 s101, s87, 0
.LBB0_276:
	v_readfirstlane_b32 s14, v62
	s_bfe_u32 s25, s14, 0x20006
	s_lshl_b32 s14, s25, 4
	s_or_b32 s15, s14, 15
	v_mov_b32_e32 v50, s15
	v_mov_b32_e32 v51, s14
	v_cndmask_b32_e32 v43, v50, v51, vcc
	v_or_b32_e32 v42, s14, v94
	v_or_b32_e32 v41, s14, v95
	v_or_b32_e32 v40, s14, v96
	v_mad_u32_u24 v26, v43, s18, v93
	v_mad_u32_u24 v27, v42, s18, v93
	v_mad_u32_u24 v28, v41, s18, v93
	v_mad_u32_u24 v29, v40, s18, v93
	v_or_b32_e32 v38, s14, v97
	v_or_b32_e32 v39, s14, v98
	v_or_b32_e32 v37, s14, v99
	v_or_b32_e32 v35, s14, v100
	v_mad_u32_u24 v30, v38, s18, v93
	v_mad_u32_u24 v31, v39, s18, v93
	v_mad_u32_u24 v32, v37, s18, v93
	v_mad_u32_u24 v33, v35, s18, v93
	ds_read_b32 v34, v26
	ds_read_b32 v36, v27
	ds_read_b32 v44, v28
	ds_read_b32 v45, v29
	ds_read_b32 v46, v30
	ds_read_b32 v47, v31
	ds_read_b32 v48, v32
	ds_read_b32 v49, v33
	global_load_dwordx4 v[2:5], v236, s[100:101]
	s_waitcnt lgkmcnt(7)
	v_lshlrev_b32_e32 v26, 16, v34
	v_and_b32_e32 v27, 0xffff0000, v34
	s_waitcnt lgkmcnt(6)
	v_lshlrev_b32_e32 v28, 16, v36
	v_and_b32_e32 v29, 0xffff0000, v36
	s_waitcnt lgkmcnt(5)
	v_lshlrev_b32_e32 v30, 16, v44
	v_and_b32_e32 v31, 0xffff0000, v44
	v_pk_add_f32 v[26:27], v[26:27], 1.0 op_sel_hi:[1,0] neg_lo:[1,0] neg_hi:[1,0]
	v_pk_add_f32 v[28:29], v[28:29], 1.0 op_sel_hi:[1,0] neg_lo:[1,0] neg_hi:[1,0]
	s_waitcnt lgkmcnt(4)
	v_lshlrev_b32_e32 v32, 16, v45
	v_and_b32_e32 v33, 0xffff0000, v45
	v_pk_mul_f32 v[26:27], v[26:27], v[28:29]
	v_pk_add_f32 v[28:29], v[30:31], 1.0 op_sel_hi:[1,0] neg_lo:[1,0] neg_hi:[1,0]
	s_waitcnt lgkmcnt(3)
	v_lshlrev_b32_e32 v44, 16, v46
	v_and_b32_e32 v45, 0xffff0000, v46
	v_pk_mul_f32 v[26:27], v[26:27], v[28:29]
	v_pk_add_f32 v[28:29], v[32:33], 1.0 op_sel_hi:[1,0] neg_lo:[1,0] neg_hi:[1,0]
	v_or_b32_e32 v36, s14, v101
	v_pk_mul_f32 v[26:27], v[26:27], v[28:29]
	v_pk_add_f32 v[28:29], v[44:45], 1.0 op_sel_hi:[1,0] neg_lo:[1,0] neg_hi:[1,0]
	v_or_b32_e32 v34, s14, v102
	v_pk_mul_f32 v[26:27], v[26:27], v[28:29]
	s_waitcnt lgkmcnt(2)
	v_lshlrev_b32_e32 v28, 16, v47
	v_and_b32_e32 v29, 0xffff0000, v47
	v_pk_add_f32 v[44:45], v[28:29], 1.0 op_sel_hi:[1,0] neg_lo:[1,0] neg_hi:[1,0]
	s_waitcnt lgkmcnt(1)
	v_lshlrev_b32_e32 v46, 16, v48
	v_and_b32_e32 v47, 0xffff0000, v48
	v_mad_u32_u24 v52, v36, s18, v93
	v_mad_u32_u24 v53, v34, s18, v93
	v_or_b32_e32 v33, s14, v103
	v_or_b32_e32 v32, s14, v104
	v_or_b32_e32 v31, s14, v105
	v_or_b32_e32 v30, s14, v106
	v_or_b32_e32 v29, s14, v107
	v_cndmask_b32_e32 v28, v51, v50, vcc
	s_waitcnt lgkmcnt(0)
	v_lshlrev_b32_e32 v48, 16, v49
	v_and_b32_e32 v49, 0xffff0000, v49
	v_mad_u32_u24 v54, v33, s18, v93
	v_mad_u32_u24 v55, v32, s18, v93
	v_mad_u32_u24 v56, v31, s18, v93
	v_mad_u32_u24 v57, v30, s18, v93
	v_mad_u32_u24 v86, v29, s18, v93
	v_mad_u32_u24 v50, v28, s18, v93
	ds_read_b32 v51, v52
	ds_read_b32 v53, v53
	ds_read_b32 v87, v54
	ds_read_b32 v131, v55
	ds_read_b32 v132, v56
	ds_read_b32 v133, v57
	ds_read_b32 v135, v86
	ds_read_b32 v137, v50
	global_load_dwordx4 v[10:13], v237, s[100:101]
	v_pk_mul_f32 v[26:27], v[26:27], v[44:45]
	v_pk_add_f32 v[44:45], v[46:47], 1.0 op_sel_hi:[1,0] neg_lo:[1,0] neg_hi:[1,0]
	s_waitcnt lgkmcnt(7)
	v_lshlrev_b32_e32 v50, 16, v51
	v_and_b32_e32 v51, 0xffff0000, v51
	v_pk_mul_f32 v[26:27], v[26:27], v[44:45]
	v_pk_add_f32 v[44:45], v[48:49], 1.0 op_sel_hi:[1,0] neg_lo:[1,0] neg_hi:[1,0]
	s_waitcnt lgkmcnt(6)
	v_lshlrev_b32_e32 v52, 16, v53
	v_and_b32_e32 v53, 0xffff0000, v53
	v_pk_mul_f32 v[26:27], v[26:27], v[44:45]
	v_pk_add_f32 v[44:45], v[50:51], 1.0 op_sel_hi:[1,0] neg_lo:[1,0] neg_hi:[1,0]
	s_waitcnt lgkmcnt(5)
	v_lshlrev_b32_e32 v54, 16, v87
	v_and_b32_e32 v55, 0xffff0000, v87
	v_pk_mul_f32 v[26:27], v[26:27], v[44:45]
	v_pk_add_f32 v[44:45], v[52:53], 1.0 op_sel_hi:[1,0] neg_lo:[1,0] neg_hi:[1,0]
	s_waitcnt lgkmcnt(4)
	v_lshlrev_b32_e32 v56, 16, v131
	v_and_b32_e32 v57, 0xffff0000, v131
	v_pk_mul_f32 v[26:27], v[26:27], v[44:45]
	v_pk_add_f32 v[44:45], v[54:55], 1.0 op_sel_hi:[1,0] neg_lo:[1,0] neg_hi:[1,0]
	s_waitcnt lgkmcnt(3)
	v_lshlrev_b32_e32 v86, 16, v132
	v_and_b32_e32 v87, 0xffff0000, v132
	v_pk_mul_f32 v[26:27], v[26:27], v[44:45]
	v_pk_add_f32 v[44:45], v[56:57], 1.0 op_sel_hi:[1,0] neg_lo:[1,0] neg_hi:[1,0]
	s_waitcnt lgkmcnt(2)
	v_lshlrev_b32_e32 v132, 16, v133
	v_and_b32_e32 v133, 0xffff0000, v133
	v_pk_mul_f32 v[26:27], v[26:27], v[44:45]
	v_pk_add_f32 v[44:45], v[86:87], 1.0 op_sel_hi:[1,0] neg_lo:[1,0] neg_hi:[1,0]
	s_waitcnt lgkmcnt(1)
	v_lshlrev_b32_e32 v134, 16, v135
	v_and_b32_e32 v135, 0xffff0000, v135
	v_pk_mul_f32 v[26:27], v[26:27], v[44:45]
	v_pk_add_f32 v[44:45], v[132:133], 1.0 op_sel_hi:[1,0] neg_lo:[1,0] neg_hi:[1,0]
	s_waitcnt lgkmcnt(0)
	v_lshlrev_b32_e32 v136, 16, v137
	v_and_b32_e32 v137, 0xffff0000, v137
	v_pk_mul_f32 v[26:27], v[26:27], v[44:45]
	v_pk_add_f32 v[44:45], v[134:135], 1.0 op_sel_hi:[1,0] neg_lo:[1,0] neg_hi:[1,0]
	v_or_b32_e32 v131, s25, v108
	v_pk_mul_f32 v[26:27], v[26:27], v[44:45]
	v_pk_add_f32 v[44:45], v[136:137], 1.0 op_sel_hi:[1,0] neg_lo:[1,0] neg_hi:[1,0]
	s_cmp_lg_u32 s25, 0
	v_mov_b32_e32 v147, v146
	v_lshl_add_u32 v131, v131, 9, v109
	v_pk_mul_f32 v[26:27], v[26:27], v[44:45]
	s_cselect_b64 s[14:15], -1, 0
	ds_write_b64 v131, v[26:27] offset:52224
	s_and_b64 s[26:27], vcc, s[14:15]
	v_mov_b64_e32 v[26:27], v[146:147]
	s_waitcnt lgkmcnt(0)
	s_barrier
	s_and_saveexec_b64 s[14:15], s[26:27]
	ds_read_b64 v[26:27], v109 offset:52224
	s_or_b64 exec, exec, s[14:15]
	s_cmp_eq_u32 s25, 0
	s_cselect_b64 s[14:15], -1, 0
	s_cmp_gt_u32 s25, 1
	v_cndmask_b32_e64 v44, 0, 1, s[14:15]
	s_cselect_b64 s[14:15], -1, 0
	v_cndmask_b32_e64 v45, 0, 1, s[14:15]
	v_cndmask_b32_e32 v44, v44, v45, vcc
	v_and_b32_e32 v44, 1, v44
	v_cmp_eq_u32_e64 s[42:43], 1, v44
	s_and_saveexec_b64 s[14:15], s[42:43]
	s_cbranch_execz .LBB0_280
	ds_read_b64 v[44:45], v130 offset:52736
	s_waitcnt lgkmcnt(0)
	v_pk_mul_f32 v[26:27], v[26:27], v[44:45]

.LBB0_284:
	s_or_b64 exec, exec, s[14:15]
	v_mul_u32_u24_e32 v43, 0x110, v43
	v_add_u32_e32 v43, v93, v43
	ds_read_b32 v45, v43
	v_mul_u32_u24_e32 v42, 0x110, v42
	v_add_u32_e32 v48, v93, v42
	v_mul_u32_u24_e32 v41, 0x110, v41
	v_add_u32_e32 v41, v93, v41
	s_waitcnt lgkmcnt(0)
	v_lshlrev_b32_e32 v44, 16, v45
	v_and_b32_e32 v45, 0xffff0000, v45
	v_sub_f32_e32 v46, 1.0, v44
	v_sub_f32_e32 v47, 1.0, v45
	v_mul_f32_e32 v46, v26, v46
	v_mul_f32_e32 v47, v27, v47
	v_max_f32_e32 v26, 0xda24260, v46
	v_max_f32_e32 v27, 0xda24260, v47
	v_rcp_f32_e32 v26, v26
	v_rcp_f32_e32 v27, v27
	v_mul_u32_u24_e32 v40, 0x110, v40
	v_mul_u32_u24_e32 v38, 0x110, v38
	v_add_u32_e32 v38, v93, v38
	v_pk_mul_f32 v[26:27], v[26:27], v[44:45]
	v_mul_u32_u24_e32 v39, 0x110, v39
	v_cvt_pk_bf16_f32 v26, v26, v27
	ds_write_b32 v43, v26
	ds_read_b32 v27, v48
	v_mul_u32_u24_e32 v37, 0x110, v37
	v_add_u32_e32 v37, v93, v37
	v_mul_u32_u24_e32 v35, 0x110, v35
	v_add_u32_e32 v35, v93, v35
	s_waitcnt lgkmcnt(0)
	v_lshlrev_b32_e32 v26, 16, v27
	v_and_b32_e32 v27, 0xffff0000, v27
	v_sub_f32_e32 v42, 1.0, v26
	v_sub_f32_e32 v43, 1.0, v27
	v_mul_f32_e32 v44, v46, v42
	v_mul_f32_e32 v45, v47, v43
	v_max_f32_e32 v42, 0xda24260, v44
	v_max_f32_e32 v43, 0xda24260, v45
	v_rcp_f32_e32 v42, v42
	v_rcp_f32_e32 v43, v43
	v_add_u32_e32 v46, v93, v40
	v_mul_u32_u24_e32 v36, 0x110, v36
	v_mul_u32_u24_e32 v34, 0x110, v34
	v_pk_mul_f32 v[26:27], v[42:43], v[26:27]
	v_mul_u32_u24_e32 v33, 0x110, v33
	v_cvt_pk_bf16_f32 v26, v26, v27
	ds_write_b32 v48, v26
	global_load_dwordx4 v[18:21], v238, s[100:101]
	ds_read_b32 v27, v41
	v_add_u32_e32 v33, v93, v33
	v_mul_u32_u24_e32 v32, 0x110, v32
	v_mul_u32_u24_e32 v31, 0x110, v31
	v_add_u32_e32 v31, v93, v31
	s_waitcnt lgkmcnt(0)
	v_lshlrev_b32_e32 v26, 16, v27
	v_and_b32_e32 v27, 0xffff0000, v27
	v_sub_f32_e32 v42, 1.0, v26
	v_sub_f32_e32 v43, 1.0, v27
	v_mul_f32_e32 v44, v44, v42
	v_mul_f32_e32 v45, v45, v43
	v_max_f32_e32 v42, 0xda24260, v44
	v_max_f32_e32 v43, 0xda24260, v45
	v_rcp_f32_e32 v42, v42
	v_rcp_f32_e32 v43, v43
	v_mul_u32_u24_e32 v30, 0x110, v30
	v_mul_u32_u24_e32 v29, 0x110, v29
	v_add_u32_e32 v29, v93, v29
	v_pk_mul_f32 v[26:27], v[42:43], v[26:27]
	v_mul_u32_u24_e32 v28, 0x110, v28
	v_cvt_pk_bf16_f32 v26, v26, v27
	ds_write_b32 v41, v26
	ds_read_b32 v27, v46
	v_mov_b64_e32 v[86:87], s[12:13]
	s_waitcnt lgkmcnt(0)
	v_lshlrev_b32_e32 v26, 16, v27
	v_and_b32_e32 v27, 0xffff0000, v27
	v_sub_f32_e32 v40, 1.0, v26
	v_sub_f32_e32 v41, 1.0, v27
	v_mul_f32_e32 v42, v44, v40
	v_mul_f32_e32 v43, v45, v41
	v_max_f32_e32 v40, 0xda24260, v42
	v_max_f32_e32 v41, 0xda24260, v43
	v_rcp_f32_e32 v40, v40
	v_rcp_f32_e32 v41, v41
	v_add_u32_e32 v44, v93, v39
	v_pk_mul_f32 v[26:27], v[40:41], v[26:27]
	s_nop 0
	v_cvt_pk_bf16_f32 v26, v26, v27
	ds_write_b32 v46, v26
	ds_read_b32 v27, v38
	s_waitcnt lgkmcnt(0)
	v_lshlrev_b32_e32 v26, 16, v27
	v_and_b32_e32 v27, 0xffff0000, v27
	v_sub_f32_e32 v40, 1.0, v26
	v_sub_f32_e32 v41, 1.0, v27
	v_mul_f32_e32 v42, v42, v40
	v_mul_f32_e32 v43, v43, v41
	v_max_f32_e32 v40, 0xda24260, v42
	v_max_f32_e32 v41, 0xda24260, v43
	v_rcp_f32_e32 v40, v40
	v_rcp_f32_e32 v41, v41
	s_nop 0
	v_pk_mul_f32 v[26:27], v[40:41], v[26:27]
	s_nop 0
	v_cvt_pk_bf16_f32 v26, v26, v27
	ds_write_b32 v38, v26
	global_load_dwordx4 v[6:9], v239, s[100:101]
	ds_read_b32 v27, v44
	s_waitcnt lgkmcnt(0)
	v_lshlrev_b32_e32 v26, 16, v27
	v_and_b32_e32 v27, 0xffff0000, v27
	v_sub_f32_e32 v38, 1.0, v26
	v_sub_f32_e32 v39, 1.0, v27
	v_mul_f32_e32 v40, v42, v38
	v_mul_f32_e32 v41, v43, v39
	v_max_f32_e32 v38, 0xda24260, v40
	v_max_f32_e32 v39, 0xda24260, v41
	v_rcp_f32_e32 v38, v38
	v_rcp_f32_e32 v39, v39
	s_nop 0
	v_pk_mul_f32 v[26:27], v[38:39], v[26:27]
	s_nop 0
	v_cvt_pk_bf16_f32 v26, v26, v27
	ds_write_b32 v44, v26
	ds_read_b32 v27, v37
	s_waitcnt lgkmcnt(0)
	v_lshlrev_b32_e32 v26, 16, v27
	v_and_b32_e32 v27, 0xffff0000, v27
	v_sub_f32_e32 v38, 1.0, v26
	v_sub_f32_e32 v39, 1.0, v27
	v_mul_f32_e32 v40, v40, v38
	v_mul_f32_e32 v41, v41, v39
	v_max_f32_e32 v38, 0xda24260, v40
	v_max_f32_e32 v39, 0xda24260, v41
	v_rcp_f32_e32 v38, v38
	v_rcp_f32_e32 v39, v39
	s_nop 0
	v_pk_mul_f32 v[26:27], v[38:39], v[26:27]
	s_nop 0
	v_cvt_pk_bf16_f32 v26, v26, v27
	ds_write_b32 v37, v26
	ds_read_b32 v27, v35
	s_waitcnt lgkmcnt(0)
	v_lshlrev_b32_e32 v26, 16, v27
	v_and_b32_e32 v27, 0xffff0000, v27
	v_sub_f32_e32 v37, 1.0, v26
	v_sub_f32_e32 v38, 1.0, v27
	v_mul_f32_e32 v37, v40, v37
	v_mul_f32_e32 v40, v41, v38
	v_max_f32_e32 v38, 0xda24260, v37
	v_max_f32_e32 v39, 0xda24260, v40
	v_rcp_f32_e32 v38, v38
	v_rcp_f32_e32 v39, v39
	v_add_u32_e32 v41, v93, v36
	v_pk_mul_f32 v[26:27], v[38:39], v[26:27]
	s_nop 0
	v_cvt_pk_bf16_f32 v26, v26, v27
	ds_write_b32 v35, v26
	global_load_dwordx4 v[14:17], v240, s[100:101]
	ds_read_b32 v27, v41
	v_add_u32_e32 v39, v93, v34
	s_waitcnt lgkmcnt(0)
	v_lshlrev_b32_e32 v26, 16, v27
	v_and_b32_e32 v27, 0xffff0000, v27
	v_sub_f32_e32 v35, 1.0, v26
	v_sub_f32_e32 v36, 1.0, v27
	v_mul_f32_e32 v35, v37, v35
	v_mul_f32_e32 v38, v40, v36
	v_max_f32_e32 v36, 0xda24260, v35
	v_max_f32_e32 v37, 0xda24260, v38
	v_rcp_f32_e32 v36, v36
	v_rcp_f32_e32 v37, v37
	s_nop 0
	v_pk_mul_f32 v[26:27], v[36:37], v[26:27]
	s_nop 0
	v_cvt_pk_bf16_f32 v26, v26, v27
	ds_write_b32 v41, v26
	ds_read_b32 v27, v39
	s_waitcnt lgkmcnt(0)
	v_lshlrev_b32_e32 v26, 16, v27
	v_and_b32_e32 v27, 0xffff0000, v27
	v_sub_f32_e32 v34, 1.0, v26
	v_sub_f32_e32 v36, 1.0, v27
	v_mul_f32_e32 v37, v35, v34
	v_mul_f32_e32 v36, v38, v36
	v_max_f32_e32 v34, 0xda24260, v37
	v_max_f32_e32 v35, 0xda24260, v36
	v_rcp_f32_e32 v34, v34
	v_rcp_f32_e32 v35, v35
	v_add_u32_e32 v38, v93, v32
	v_pk_mul_f32 v[26:27], v[34:35], v[26:27]
	s_nop 0
	v_cvt_pk_bf16_f32 v26, v26, v27
	ds_write_b32 v39, v26
	ds_read_b32 v27, v33
	s_waitcnt lgkmcnt(0)
	v_lshlrev_b32_e32 v26, 16, v27
	v_and_b32_e32 v27, 0xffff0000, v27
	v_sub_f32_e32 v34, 1.0, v26
	v_sub_f32_e32 v35, 1.0, v27
	v_mul_f32_e32 v37, v37, v34
	v_mul_f32_e32 v36, v36, v35
	v_max_f32_e32 v34, 0xda24260, v37
	v_max_f32_e32 v35, 0xda24260, v36
	v_rcp_f32_e32 v34, v34
	v_rcp_f32_e32 v35, v35
	s_nop 0
	v_pk_mul_f32 v[26:27], v[34:35], v[26:27]
	s_nop 0
	v_cvt_pk_bf16_f32 v26, v26, v27
	ds_write_b32 v33, v26
	global_load_dwordx4 v[22:25], v241, s[100:101]
	ds_read_b32 v27, v38
	s_waitcnt lgkmcnt(0)
	v_lshlrev_b32_e32 v26, 16, v27
	v_and_b32_e32 v27, 0xffff0000, v27
	v_sub_f32_e32 v32, 1.0, v26
	v_sub_f32_e32 v33, 1.0, v27
	v_mul_f32_e32 v34, v37, v32
	v_mul_f32_e32 v35, v36, v33
	v_max_f32_e32 v32, 0xda24260, v34
	v_max_f32_e32 v33, 0xda24260, v35
	v_rcp_f32_e32 v32, v32
	v_rcp_f32_e32 v33, v33
	v_add_u32_e32 v36, v93, v30
	v_pk_mul_f32 v[26:27], v[32:33], v[26:27]
	s_nop 0
	v_cvt_pk_bf16_f32 v26, v26, v27
	ds_write_b32 v38, v26
	ds_read_b32 v27, v31
	s_waitcnt lgkmcnt(0)
	v_lshlrev_b32_e32 v26, 16, v27
	v_and_b32_e32 v27, 0xffff0000, v27
	v_sub_f32_e32 v32, 1.0, v26
	v_sub_f32_e32 v33, 1.0, v27
	v_mul_f32_e32 v34, v34, v32
	v_mul_f32_e32 v35, v35, v33
	v_max_f32_e32 v32, 0xda24260, v34
	v_max_f32_e32 v33, 0xda24260, v35
	v_rcp_f32_e32 v32, v32
	v_rcp_f32_e32 v33, v33
	s_nop 0
	v_pk_mul_f32 v[26:27], v[32:33], v[26:27]
	s_nop 0
	v_cvt_pk_bf16_f32 v26, v26, v27
	ds_write_b32 v31, v26
	ds_read_b32 v27, v36
	s_waitcnt lgkmcnt(0)
	v_lshlrev_b32_e32 v26, 16, v27
	v_and_b32_e32 v27, 0xffff0000, v27
	v_sub_f32_e32 v30, 1.0, v26
	v_sub_f32_e32 v31, 1.0, v27
	v_mul_f32_e32 v32, v34, v30
	v_mul_f32_e32 v33, v35, v31
	v_max_f32_e32 v30, 0xda24260, v32
	v_max_f32_e32 v31, 0xda24260, v33
	v_rcp_f32_e32 v30, v30
	v_rcp_f32_e32 v31, v31
	v_add_u32_e32 v34, v93, v28
	v_pk_mul_f32 v[26:27], v[30:31], v[26:27]
	s_nop 0
	v_cvt_pk_bf16_f32 v26, v26, v27
	ds_write_b32 v36, v26
	ds_read_b32 v27, v29
	s_waitcnt lgkmcnt(0)
	v_lshlrev_b32_e32 v26, 16, v27
	v_and_b32_e32 v27, 0xffff0000, v27
	v_sub_f32_e32 v30, 1.0, v26
	v_sub_f32_e32 v31, 1.0, v27
	v_mul_f32_e32 v32, v32, v30
	v_mul_f32_e32 v33, v33, v31
	v_max_f32_e32 v30, 0xda24260, v32
	v_max_f32_e32 v31, 0xda24260, v33
	v_rcp_f32_e32 v30, v30
	v_rcp_f32_e32 v31, v31
	s_nop 0
	v_pk_mul_f32 v[26:27], v[30:31], v[26:27]
	s_nop 0
	v_cvt_pk_bf16_f32 v26, v26, v27
	ds_write_b32 v29, v26
	ds_read_b32 v27, v34
	s_waitcnt lgkmcnt(0)
	v_lshlrev_b32_e32 v26, 16, v27
	v_and_b32_e32 v27, 0xffff0000, v27
	v_sub_f32_e32 v28, 1.0, v26
	v_sub_f32_e32 v29, 1.0, v27
	v_mul_f32_e32 v28, v32, v28
	v_mul_f32_e32 v29, v33, v29
	v_max_f32_e32 v28, 0xda24260, v28
	v_max_f32_e32 v29, 0xda24260, v29
	v_rcp_f32_e32 v28, v28
	v_rcp_f32_e32 v29, v29
	s_nop 0
	v_pk_mul_f32 v[26:27], v[28:29], v[26:27]
	s_nop 0
	v_cvt_pk_bf16_f32 v26, v26, v27
	ds_write_b32 v34, v26
	s_waitcnt lgkmcnt(0)
	s_barrier
	s_and_saveexec_b64 s[42:43], s[40:41]
	s_cbranch_execz .LBB0_273
	ds_read2st64_b32 v[26:27], v110 offset0:204 offset1:206
	ds_read2st64_b32 v[28:29], v110 offset0:208 offset1:210
	s_bfe_i64 s[14:15], s[12:13], 0x200000
	v_mov_b64_e32 v[86:87], s[14:15]
	s_waitcnt lgkmcnt(1)
	v_mov_b32_e32 v30, v26
	s_waitcnt lgkmcnt(0)
	v_mov_b32_e32 v31, v28
	v_mov_b32_e32 v28, v27
	v_pk_mul_f32 v[26:27], v[30:31], v[28:29]
	s_nop 0
	v_mul_f32_e32 v26, v26, v27
	global_store_dword v[84:85], v26, off
	s_branch .LBB0_273
